# P5|P6 seam: workgroup only arrives at the 4-WG counter; out-proj K-loop starts on the attention half of MIX and waits for the group counter inside the K-loop before staging the first GLU-half K-tile
# speedup vs baseline: 1.0122x; 1.0018x over previous
; __device__ __forceinline__ unsigned xb_ld(unsigned* p)              { return __hip_atomic_load(p, __ATOMIC_RELAXED, __HIP_MEMORY_SCOPE_AGENT); }
; __device__ __forceinline__ unsigned xb_add(unsigned* p, unsigned v) { return __hip_atomic_fetch_add(p, v, __ATOMIC_RELAXED, __HIP_MEMORY_SCOPE_AGENT); }
; #define XB_SPIN(cond, bar) do { unsigned _sp = 0; while (cond) { __builtin_amdgcn_s_sleep(1); \
;     if ((++_sp & 255u) == 0u) { if (xb_ld(&(bar)[XB_TMO])) break; if (_sp > XB_SPIN_CAP) { atomicAdd(&(bar)[XB_TMO], 1u); break; } } } } while (0)
; __device__ __forceinline__ void xcd_barrier(const XcdBarrier& b) {
;     asm volatile("s_waitcnt vmcnt(0)" ::: "memory");
;     __syncthreads();
;     if (threadIdx.x == 0) {
;         unsigned* bar = b.bar;
;         __builtin_amdgcn_s_waitcnt(0);
;         unsigned nloc = b.st[0], nx = b.st[1];
;         if (nloc == 0u) { xcd_barrier_complete(bar, b.x, nloc, nx); b.st[0] = nloc; b.st[1] = nx; }
;         const unsigned old = xb_add(&bar[XB_XSUB(b.x)], 1u);
;         const unsigned gen = old / nloc;
;         if (old + 1u == (gen + 1u) * nloc) {
;             __builtin_amdgcn_fence(__ATOMIC_RELEASE, "agent");
;             asm volatile("s_waitcnt vmcnt(0)" ::: "memory");
;             const unsigned og = xb_add(&bar[XB_TOP], 1u);
;             const unsigned tg = og / nx;
;             __builtin_amdgcn_fence(__ATOMIC_ACQUIRE, "agent");
;             if (og + 1u == (tg + 1u) * nx) xb_add(&bar[XB_TOPGEN], 1u);
;             else XB_SPIN(xb_ld(&bar[XB_TOPGEN]) == tg, bar);
;             xb_add(&bar[XB_XGEN(b.x)], 1u);
.LBB0_626:
	s_waitcnt vmcnt(0)
	s_waitcnt vmcnt(0) lgkmcnt(0)
	s_barrier
	s_mov_b64 s[4:5], exec
	v_readlane_b32 s8, v253, 41
	v_readlane_b32 s9, v253, 42
	s_and_b64 s[8:9], s[4:5], s[8:9]
	s_mov_b64 exec, s[8:9]
	s_cbranch_execz .LBB0_678
	s_waitcnt vmcnt(0) lgkmcnt(0)
	v_readlane_b32 s78, v254, 29
	v_readlane_b32 s79, v254, 30
	v_readlane_b32 s77, v253, 0
	v_readlane_b32 s76, v254, 53
	s_add_u32 s78, s78, 0x6c00
	s_addc_u32 s79, s79, 0
	s_and_b32 s77, s77, 63
	s_lshl_b32 s77, s77, 8
	s_add_u32 s76, s76, 1
	s_lshl_b32 s76, s76, 2
	v_mov_b32_e32 v0, s77
	v_mov_b32_e32 v1, 1
	s_nop 1
	global_atomic_add v0, v1, s[78:79]

; #define PG8_STAGE(bufoff, gbase, voff) do { _Pragma("unroll") for (int _i = 0; _i < 2; ++_i) \
;         __builtin_amdgcn_global_load_lds((const unsigned*)((const char*)(gbase) + (voff)[_i]), (LAS unsigned*)(lds + (bufoff) + ldsw + _i * 8192), 16, 0, 0); } while (0)
; #define PG8_LDA(dst, b, h) do { _Pragma("unroll") for (int m = 0; m < 4; ++m) _Pragma("unroll") for (int k = 0; k < 2; ++k) dst[m][k] = *(const LAS bf16x8*)(lds + PG8_SA(b, h) + aoff + m * 2048 + k * 1024); } while (0)
; #define PG8_LDB(dst, b, h) do { _Pragma("unroll") for (int n = 0; n < 2; ++n) _Pragma("unroll") for (int k = 0; k < 2; ++k) dst[n][k] = *(const LAS bf16x8*)(lds + PG8_SB(b, h) + boff + n * 2048 + k * 1024); } while (0)
; template <class Epi, class Sched, bool ALIGN_EPI = true, bool SP2 = true, class Pre = NoPre>
; __device__ __forceinline__ void gemm_phase(LAS unsigned char* lds, const Gemm g, const Sched& S, const Epi& E, const Pre& pre = Pre()) {
;     ...
;         for (int t = 0; t < nt; t += 2) {
;             S.k_hook(t, wid);
;             const bool last = (t == nt - 2);
;             const char* a1 = cA + (size_t)(t + 1) * kstep;
;             const char* a2 = last ? nA : cA + (size_t)(t + 2) * kstep; const char* b2 = last ? nB : cB + (size_t)(t + 2) * kstep;
;             const char* a3 = a2 + kstep; const char* b3 = b2 + kstep;
;             if constexpr (SP2) {
;             PG8_LDB(B0, 0, 0); PG8_LDB(B1, 0, 1); PG8_SCHED; PG8_LDA(At, 0, 0); PG8_STAGE(PG8_SA(1, 1), a1 + hsA, voffA);
;             PG8_WAIT_V(8); PG8_WAIT_L(0); PG8_BAR; PG8_MMA(0, 0, At, B0); PG8_MMA(0, 1, At, B1); PG8_BAR; PG8_SCHED;
;             PG8_LDA(At, 0, 1); PG8_STAGE(PG8_SB(0, 0), b2, voffB); PG8_STAGE(PG8_SB(0, 1), b2 + hsB, voffB); PG8_STAGE(PG8_SA(0, 0), a2, voffA);
;             PG8_WAIT_V(8); PG8_WAIT_L(0); PG8_BAR; PG8_MMA(1, 0, At, B0); PG8_MMA(1, 1, At, B1); PG8_BAR; PG8_SCHED;
;             PG8_LDB(B0, 1, 0); PG8_LDB(B1, 1, 1); PG8_SCHED; PG8_LDA(At, 1, 0); PG8_STAGE(PG8_SA(0, 1), a2 + hsA, voffA);
;             PG8_WAIT_V(8); PG8_WAIT_L(0); PG8_BAR; PG8_MMA(0, 0, At, B0); PG8_MMA(0, 1, At, B1); PG8_BAR; PG8_SCHED;
;             PG8_LDA(At, 1, 1); PG8_STAGE(PG8_SB(1, 0), b3, voffB); PG8_STAGE(PG8_SB(1, 1), b3 + hsB, voffB); PG8_STAGE(PG8_SA(1, 0), a3, voffA);
;             PG8_WAIT_V(8); PG8_WAIT_L(0); PG8_BAR; PG8_MMA(1, 0, At, B0); PG8_MMA(1, 1, At, B1); PG8_BAR; PG8_SCHED;
.LBB0_697:
	s_cmp_lg_u32 s84, 4
	s_cbranch_scc1 .Lp6g_skip
	v_readlane_b32 s70, v253, 41
	v_readlane_b32 s71, v253, 42
	s_mov_b64 s[98:99], exec
	s_and_b64 s[70:71], s[98:99], s[70:71]
	s_cbranch_scc0 .Lp6g_bar
	s_mov_b64 exec, s[70:71]
	v_readlane_b32 s78, v254, 29
	v_readlane_b32 s79, v254, 30
	v_readlane_b32 s77, v253, 0
	v_readlane_b32 s76, v254, 53
	s_add_u32 s78, s78, 0x6c00
	s_addc_u32 s79, s79, 0
	s_and_b32 s77, s77, 63
	s_lshl_b32 s77, s77, 8
	s_add_u32 s76, s76, 1
	s_lshl_b32 s76, s76, 2
	s_mov_b32 s3, 0
	s_nop 2
.Lp6g_poll:
	v_mov_b32_e32 v250, s77
	global_load_dword v250, v250, s[78:79] sc1
	s_waitcnt vmcnt(0)
	v_readfirstlane_b32 s26, v250
	s_cmp_ge_u32 s26, s76
	s_cbranch_scc1 .Lp6g_done
	s_sleep 1
	s_add_u32 s3, s3, 1
	s_cmp_lt_u32 s3, 0x8000
	s_cbranch_scc1 .Lp6g_poll
.Lp6g_done:
	buffer_inv sc1
	s_mov_b64 exec, s[98:99]
.Lp6g_bar:
	s_barrier
.Lp6g_skip:
	s_add_u32 s30, vcc_lo, 0xfffc0080
	s_addc_u32 s31, vcc_hi, -1
	s_add_i32 s85, 0, 0x10000
	s_cmp_eq_u32 s84, 12
	s_cselect_b32 s83, s39, s31
	s_cselect_b32 s82, s45, s30
	s_cselect_b32 s31, s23, s58
	s_cselect_b32 s30, s46, s47
	s_add_i32 s93, 0, 0x14000
	v_add_u32_e32 v100, s85, v245
	v_add_u32_e32 v148, s93, v245
	ds_read_b128 v[64:67], v100
	ds_read_b128 v[76:79], v100 offset:1024
	ds_read_b128 v[88:91], v100 offset:2048
	ds_read_b128 v[100:103], v100 offset:3072
	ds_read_b128 v[112:115], v148
	ds_read_b128 v[124:127], v148 offset:1024
	ds_read_b128 v[136:139], v148 offset:2048
	ds_read_b128 v[148:151], v148 offset:3072
	v_lshl_add_u64 v[192:193], vcc, 0, v[220:221]
	s_add_i32 m0, s9, 0xc000
	ds_read_b128 v[160:163], v247
	ds_read_b128 v[164:167], v247 offset:1024
	ds_read_b128 v[168:171], v247 offset:2048
	ds_read_b128 v[172:175], v247 offset:3072
	ds_read_b128 v[176:179], v247 offset:4096
	ds_read_b128 v[180:183], v247 offset:5120
	ds_read_b128 v[184:187], v247 offset:6144
	ds_read_b128 v[188:191], v247 offset:7168
	global_load_lds_dwordx4 v[192:193], off
	v_lshl_add_u64 v[192:193], vcc, 0, v[218:219]
	s_add_i32 m0, s9, 0xe000
	s_nop 0
	global_load_lds_dwordx4 v[192:193], off
	s_waitcnt vmcnt(8)
	s_waitcnt lgkmcnt(0)
	s_barrier
	s_setprio 1
	s_waitcnt lgkmcnt(0)
	v_mfma_f32_16x16x32_bf16 v[156:159], v[64:67], v[160:163], v[156:159]
	v_mfma_f32_16x16x32_bf16 v[152:155], v[88:91], v[160:163], v[152:155]
	v_mfma_f32_16x16x32_bf16 v[132:135], v[64:67], v[168:171], v[132:135]
	v_mfma_f32_16x16x32_bf16 v[128:131], v[88:91], v[168:171], v[128:131]
	v_mfma_f32_16x16x32_bf16 v[108:111], v[64:67], v[176:179], v[108:111]
	v_mfma_f32_16x16x32_bf16 v[104:107], v[88:91], v[176:179], v[104:107]
	v_mfma_f32_16x16x32_bf16 v[84:87], v[64:67], v[184:187], v[84:87]
	v_mfma_f32_16x16x32_bf16 v[80:83], v[88:91], v[184:187], v[80:83]
	v_mfma_f32_16x16x32_bf16 v[156:159], v[76:79], v[164:167], v[156:159]
	v_mfma_f32_16x16x32_bf16 v[152:155], v[100:103], v[164:167], v[152:155]
	v_mfma_f32_16x16x32_bf16 v[132:135], v[76:79], v[172:175], v[132:135]
	v_mfma_f32_16x16x32_bf16 v[128:131], v[100:103], v[172:175], v[128:131]
	v_mfma_f32_16x16x32_bf16 v[108:111], v[76:79], v[180:183], v[108:111]
	v_mfma_f32_16x16x32_bf16 v[104:107], v[100:103], v[180:183], v[104:107]
	v_mfma_f32_16x16x32_bf16 v[84:87], v[76:79], v[188:191], v[84:87]
	v_mfma_f32_16x16x32_bf16 v[80:83], v[100:103], v[188:191], v[80:83]
	s_setprio 0
	s_setprio 1
	v_mfma_f32_16x16x32_bf16 v[144:147], v[112:115], v[160:163], v[144:147]
	v_mfma_f32_16x16x32_bf16 v[140:143], v[136:139], v[160:163], v[140:143]
	v_mfma_f32_16x16x32_bf16 v[120:123], v[112:115], v[168:171], v[120:123]
	v_mfma_f32_16x16x32_bf16 v[116:119], v[136:139], v[168:171], v[116:119]
	v_mfma_f32_16x16x32_bf16 v[96:99], v[112:115], v[176:179], v[96:99]
	v_mfma_f32_16x16x32_bf16 v[92:95], v[136:139], v[176:179], v[92:95]
	v_mfma_f32_16x16x32_bf16 v[72:75], v[112:115], v[184:187], v[72:75]
	v_mfma_f32_16x16x32_bf16 v[68:71], v[136:139], v[184:187], v[68:71]
	v_mfma_f32_16x16x32_bf16 v[144:147], v[124:127], v[164:167], v[144:147]
	v_mfma_f32_16x16x32_bf16 v[140:143], v[148:151], v[164:167], v[140:143]
	v_mfma_f32_16x16x32_bf16 v[120:123], v[124:127], v[172:175], v[120:123]
	v_mfma_f32_16x16x32_bf16 v[116:119], v[148:151], v[172:175], v[116:119]
	v_mfma_f32_16x16x32_bf16 v[96:99], v[124:127], v[180:183], v[96:99]
	v_mfma_f32_16x16x32_bf16 v[92:95], v[148:151], v[180:183], v[92:95]
	v_mfma_f32_16x16x32_bf16 v[72:75], v[124:127], v[188:191], v[72:75]
	v_mfma_f32_16x16x32_bf16 v[68:71], v[148:151], v[188:191], v[68:71]
	s_setprio 0
	s_barrier
	s_add_i32 s85, s85, s7
	v_lshl_add_u64 v[192:193], s[30:31], 0, v[200:201]
	s_mov_b32 m0, s85
	ds_read_b128 v[160:163], v247 offset:16384
	ds_read_b128 v[164:167], v247 offset:17408
	ds_read_b128 v[168:171], v247 offset:18432
	ds_read_b128 v[172:175], v247 offset:19456
	ds_read_b128 v[176:179], v247 offset:20480
	ds_read_b128 v[180:183], v247 offset:21504
	ds_read_b128 v[184:187], v247 offset:22528
	ds_read_b128 v[188:191], v247 offset:23552
	global_load_lds_dwordx4 v[192:193], off
	s_add_i32 m0, s85, 0x2000
	s_add_u32 s96, s30, 0x40000
	v_lshl_add_u64 v[194:195], s[30:31], 0, v[216:217]
	s_addc_u32 s97, s31, 0
	s_add_i32 s85, s93, s7
	global_load_lds_dwordx4 v[194:195], off
	v_lshl_add_u64 v[196:197], s[96:97], 0, v[200:201]
	s_mov_b32 m0, s85
	v_lshl_add_u64 v[198:199], s[82:83], 0, v[214:215]
	global_load_lds_dwordx4 v[196:197], off
	v_lshl_add_u64 v[196:197], s[96:97], 0, v[216:217]
	s_add_i32 m0, s85, 0x2000
	s_nop 0
	global_load_lds_dwordx4 v[196:197], off
	v_lshl_add_u64 v[196:197], s[82:83], 0, v[212:213]
	s_mov_b32 m0, s9
	s_nop 0
	global_load_lds_dwordx4 v[196:197], off
	s_mov_b32 m0, s13
	s_nop 0
	global_load_lds_dwordx4 v[198:199], off
	s_waitcnt vmcnt(8)
	s_waitcnt lgkmcnt(0)
	s_barrier
; #define PG8_STAGE(bufoff, gbase, voff) do { _Pragma("unroll") for (int _i = 0; _i < 2; ++_i) \
;         __builtin_amdgcn_global_load_lds((const unsigned*)((const char*)(gbase) + (voff)[_i]), (LAS unsigned*)(lds + (bufoff) + ldsw + _i * 8192), 16, 0, 0); } while (0)
; #define PG8_LDA(dst, b, h) do { _Pragma("unroll") for (int m = 0; m < 4; ++m) _Pragma("unroll") for (int k = 0; k < 2; ++k) dst[m][k] = *(const LAS bf16x8*)(lds + PG8_SA(b, h) + aoff + m * 2048 + k * 1024); } while (0)
; #define PG8_LDB(dst, b, h) do { _Pragma("unroll") for (int n = 0; n < 2; ++n) _Pragma("unroll") for (int k = 0; k < 2; ++k) dst[n][k] = *(const LAS bf16x8*)(lds + PG8_SB(b, h) + boff + n * 2048 + k * 1024); } while (0)
; #define PG8_MMA(ai, bj, At, Bt) do { __builtin_amdgcn_s_setprio(1); _Pragma("unroll") for (int m = 0; m < 4; ++m) _Pragma("unroll") for (int n = 0; n < 2; ++n) _Pragma("unroll") for (int k = 0; k < 2; ++k) \
;         acc[ai][bj][m][n] = __builtin_amdgcn_mfma_f32_16x16x32_bf16(Bt[n][k], At[m][k], acc[ai][bj][m][n], 0, 0, 0); __builtin_amdgcn_s_setprio(0); } while (0)
; #define PG8_WAIT_V(n) asm volatile("s_waitcnt vmcnt(" #n ")" ::: "memory")
; #define PG8_WAIT_L(n) asm volatile("s_waitcnt lgkmcnt(" #n ")" ::: "memory")
; #define PG8_BAR __builtin_amdgcn_s_barrier()
; #define PG8_SCHED __builtin_amdgcn_sched_barrier(0)
; template <class Epi, class Sched, bool ALIGN_EPI = true, bool SP2 = true, class Pre = NoPre>
; __device__ __forceinline__ void gemm_phase(LAS unsigned char* lds, const Gemm g, const Sched& S, const Epi& E, const Pre& pre = Pre()) {
;     ...
;             PG8_LDB(B0, 0, 0); PG8_LDB(B1, 0, 1); PG8_SCHED; PG8_LDA(At, 0, 0); PG8_STAGE(PG8_SA(1, 1), a1 + hsA, voffA);
;             PG8_WAIT_V(8); PG8_WAIT_L(0); PG8_BAR; PG8_MMA(0, 0, At, B0); PG8_MMA(0, 1, At, B1); PG8_BAR; PG8_SCHED;
;             PG8_LDA(At, 0, 1); PG8_STAGE(PG8_SB(0, 0), b2, voffB); PG8_STAGE(PG8_SB(0, 1), b2 + hsB, voffB); PG8_STAGE(PG8_SA(0, 0), a2, voffA);
;             PG8_WAIT_V(8); PG8_WAIT_L(0); PG8_BAR; PG8_MMA(1, 0, At, B0); PG8_MMA(1, 1, At, B1); PG8_BAR; PG8_SCHED;
;             PG8_LDB(B0, 1, 0); PG8_LDB(B1, 1, 1); PG8_SCHED; PG8_LDA(At, 1, 0); PG8_STAGE(PG8_SA(0, 1), a2 + hsA, voffA);
;             PG8_WAIT_V(8); PG8_WAIT_L(0); PG8_BAR; PG8_MMA(0, 0, At, B0); PG8_MMA(0, 1, At, B1); PG8_BAR; PG8_SCHED;
	s_setprio 1
	s_waitcnt lgkmcnt(0)
	v_mfma_f32_16x16x32_bf16 v[60:63], v[64:67], v[160:163], v[60:63]
	v_mfma_f32_16x16x32_bf16 v[56:59], v[88:91], v[160:163], v[56:59]
	v_mfma_f32_16x16x32_bf16 v[44:47], v[64:67], v[168:171], v[44:47]
	v_mfma_f32_16x16x32_bf16 v[40:43], v[88:91], v[168:171], v[40:43]
	v_mfma_f32_16x16x32_bf16 v[28:31], v[64:67], v[176:179], v[28:31]
	v_mfma_f32_16x16x32_bf16 v[24:27], v[88:91], v[176:179], v[24:27]
	v_mfma_f32_16x16x32_bf16 v[12:15], v[64:67], v[184:187], v[12:15]
	v_mfma_f32_16x16x32_bf16 v[8:11], v[88:91], v[184:187], v[8:11]
	v_mfma_f32_16x16x32_bf16 v[60:63], v[76:79], v[164:167], v[60:63]
	v_mfma_f32_16x16x32_bf16 v[56:59], v[100:103], v[164:167], v[56:59]
	v_mfma_f32_16x16x32_bf16 v[44:47], v[76:79], v[172:175], v[44:47]
	v_mfma_f32_16x16x32_bf16 v[40:43], v[100:103], v[172:175], v[40:43]
	v_mfma_f32_16x16x32_bf16 v[28:31], v[76:79], v[180:183], v[28:31]
	v_mfma_f32_16x16x32_bf16 v[24:27], v[100:103], v[180:183], v[24:27]
	v_mfma_f32_16x16x32_bf16 v[12:15], v[76:79], v[188:191], v[12:15]
	v_mfma_f32_16x16x32_bf16 v[8:11], v[100:103], v[188:191], v[8:11]
	s_setprio 0
	s_setprio 1
	v_mfma_f32_16x16x32_bf16 v[52:55], v[112:115], v[160:163], v[52:55]
	v_mfma_f32_16x16x32_bf16 v[48:51], v[136:139], v[160:163], v[48:51]
	v_mfma_f32_16x16x32_bf16 v[36:39], v[112:115], v[168:171], v[36:39]
	v_mfma_f32_16x16x32_bf16 v[32:35], v[136:139], v[168:171], v[32:35]
	v_mfma_f32_16x16x32_bf16 v[20:23], v[112:115], v[176:179], v[20:23]
	v_mfma_f32_16x16x32_bf16 v[16:19], v[136:139], v[176:179], v[16:19]
	v_mfma_f32_16x16x32_bf16 v[4:7], v[112:115], v[184:187], v[4:7]
	v_mfma_f32_16x16x32_bf16 v[0:3], v[136:139], v[184:187], v[0:3]
	v_mfma_f32_16x16x32_bf16 v[52:55], v[124:127], v[164:167], v[52:55]
	v_mfma_f32_16x16x32_bf16 v[48:51], v[148:151], v[164:167], v[48:51]
	v_mfma_f32_16x16x32_bf16 v[36:39], v[124:127], v[172:175], v[36:39]
	v_mfma_f32_16x16x32_bf16 v[32:35], v[148:151], v[172:175], v[32:35]
	v_mfma_f32_16x16x32_bf16 v[20:23], v[124:127], v[180:183], v[20:23]
	v_mfma_f32_16x16x32_bf16 v[16:19], v[148:151], v[180:183], v[16:19]
	v_mfma_f32_16x16x32_bf16 v[4:7], v[124:127], v[188:191], v[4:7]
	v_mfma_f32_16x16x32_bf16 v[0:3], v[148:151], v[188:191], v[0:3]
	s_setprio 0
	s_barrier
	s_add_i32 s85, 0, 0x18000
	s_add_i32 s93, 0, 0x1c000
	v_add_u32_e32 v100, s85, v245
	v_add_u32_e32 v148, s93, v245
	ds_read_b128 v[64:67], v100
	ds_read_b128 v[76:79], v100 offset:1024
	ds_read_b128 v[88:91], v100 offset:2048
	ds_read_b128 v[100:103], v100 offset:3072
	ds_read_b128 v[112:115], v148
	ds_read_b128 v[124:127], v148 offset:1024
	ds_read_b128 v[136:139], v148 offset:2048
	ds_read_b128 v[148:151], v148 offset:3072
	s_add_u32 s82, s82, 0x40000
	s_addc_u32 s83, s83, 0
	s_mov_b32 m0, s15
	v_lshl_add_u64 v[222:223], s[82:83], 0, v[212:213]
	ds_read_b128 v[160:163], v247 offset:32768
	ds_read_b128 v[164:167], v247 offset:33792
	ds_read_b128 v[168:171], v247 offset:34816
	ds_read_b128 v[172:175], v247 offset:35840
	ds_read_b128 v[176:179], v247 offset:36864
	ds_read_b128 v[180:183], v247 offset:37888
	ds_read_b128 v[184:187], v247 offset:38912
	ds_read_b128 v[188:191], v247 offset:39936
	global_load_lds_dwordx4 v[222:223], off
	v_lshl_add_u64 v[222:223], s[82:83], 0, v[214:215]
	s_mov_b32 m0, s27
	s_nop 0
	global_load_lds_dwordx4 v[222:223], off
	s_waitcnt vmcnt(8)
	s_waitcnt lgkmcnt(0)
	s_barrier
	s_setprio 1
	s_waitcnt lgkmcnt(0)
	v_mfma_f32_16x16x32_bf16 v[156:159], v[64:67], v[160:163], v[156:159]
	v_mfma_f32_16x16x32_bf16 v[152:155], v[88:91], v[160:163], v[152:155]
	v_mfma_f32_16x16x32_bf16 v[132:135], v[64:67], v[168:171], v[132:135]
	v_mfma_f32_16x16x32_bf16 v[128:131], v[88:91], v[168:171], v[128:131]
	v_mfma_f32_16x16x32_bf16 v[108:111], v[64:67], v[176:179], v[108:111]
	v_mfma_f32_16x16x32_bf16 v[104:107], v[88:91], v[176:179], v[104:107]
	v_mfma_f32_16x16x32_bf16 v[84:87], v[64:67], v[184:187], v[84:87]
	v_mfma_f32_16x16x32_bf16 v[80:83], v[88:91], v[184:187], v[80:83]
	v_mfma_f32_16x16x32_bf16 v[156:159], v[76:79], v[164:167], v[156:159]
	v_mfma_f32_16x16x32_bf16 v[152:155], v[100:103], v[164:167], v[152:155]
	v_mfma_f32_16x16x32_bf16 v[132:135], v[76:79], v[172:175], v[132:135]
	v_mfma_f32_16x16x32_bf16 v[128:131], v[100:103], v[172:175], v[128:131]
	v_mfma_f32_16x16x32_bf16 v[108:111], v[76:79], v[180:183], v[108:111]
	v_mfma_f32_16x16x32_bf16 v[104:107], v[100:103], v[180:183], v[104:107]
	v_mfma_f32_16x16x32_bf16 v[84:87], v[76:79], v[188:191], v[84:87]
	v_mfma_f32_16x16x32_bf16 v[80:83], v[100:103], v[188:191], v[80:83]
	s_setprio 0
	s_setprio 1
	v_mfma_f32_16x16x32_bf16 v[144:147], v[112:115], v[160:163], v[144:147]
	v_mfma_f32_16x16x32_bf16 v[140:143], v[136:139], v[160:163], v[140:143]
	v_mfma_f32_16x16x32_bf16 v[120:123], v[112:115], v[168:171], v[120:123]
	v_mfma_f32_16x16x32_bf16 v[116:119], v[136:139], v[168:171], v[116:119]
	v_mfma_f32_16x16x32_bf16 v[96:99], v[112:115], v[176:179], v[96:99]
	v_mfma_f32_16x16x32_bf16 v[92:95], v[136:139], v[176:179], v[92:95]
	v_mfma_f32_16x16x32_bf16 v[72:75], v[112:115], v[184:187], v[72:75]
	v_mfma_f32_16x16x32_bf16 v[68:71], v[136:139], v[184:187], v[68:71]
	v_mfma_f32_16x16x32_bf16 v[144:147], v[124:127], v[164:167], v[144:147]
	v_mfma_f32_16x16x32_bf16 v[140:143], v[148:151], v[164:167], v[140:143]
	v_mfma_f32_16x16x32_bf16 v[120:123], v[124:127], v[172:175], v[120:123]
	v_mfma_f32_16x16x32_bf16 v[116:119], v[148:151], v[172:175], v[116:119]
	v_mfma_f32_16x16x32_bf16 v[96:99], v[124:127], v[180:183], v[96:99]
	v_mfma_f32_16x16x32_bf16 v[92:95], v[148:151], v[180:183], v[92:95]
	v_mfma_f32_16x16x32_bf16 v[72:75], v[124:127], v[188:191], v[72:75]
	v_mfma_f32_16x16x32_bf16 v[68:71], v[148:151], v[188:191], v[68:71]
	s_setprio 0
	s_barrier
; #define PG8_STAGE(bufoff, gbase, voff) do { _Pragma("unroll") for (int _i = 0; _i < 2; ++_i) \
;         __builtin_amdgcn_global_load_lds((const unsigned*)((const char*)(gbase) + (voff)[_i]), (LAS unsigned*)(lds + (bufoff) + ldsw + _i * 8192), 16, 0, 0); } while (0)
; #define PG8_LDA(dst, b, h) do { _Pragma("unroll") for (int m = 0; m < 4; ++m) _Pragma("unroll") for (int k = 0; k < 2; ++k) dst[m][k] = *(const LAS bf16x8*)(lds + PG8_SA(b, h) + aoff + m * 2048 + k * 1024); } while (0)
; #define PG8_LDB(dst, b, h) do { _Pragma("unroll") for (int n = 0; n < 2; ++n) _Pragma("unroll") for (int k = 0; k < 2; ++k) dst[n][k] = *(const LAS bf16x8*)(lds + PG8_SB(b, h) + boff + n * 2048 + k * 1024); } while (0)
; #define PG8_MMA(ai, bj, At, Bt) do { __builtin_amdgcn_s_setprio(1); _Pragma("unroll") for (int m = 0; m < 4; ++m) _Pragma("unroll") for (int n = 0; n < 2; ++n) _Pragma("unroll") for (int k = 0; k < 2; ++k) \
;         acc[ai][bj][m][n] = __builtin_amdgcn_mfma_f32_16x16x32_bf16(Bt[n][k], At[m][k], acc[ai][bj][m][n], 0, 0, 0); __builtin_amdgcn_s_setprio(0); } while (0)
; #define PG8_WAIT_V(n) asm volatile("s_waitcnt vmcnt(" #n ")" ::: "memory")
; #define PG8_WAIT_L(n) asm volatile("s_waitcnt lgkmcnt(" #n ")" ::: "memory")
; #define PG8_BAR __builtin_amdgcn_s_barrier()
; #define PG8_SCHED __builtin_amdgcn_sched_barrier(0)
; template <class Epi, class Sched, bool ALIGN_EPI = true, bool SP2 = true, class Pre = NoPre>
; __device__ __forceinline__ void gemm_phase(LAS unsigned char* lds, const Gemm g, const Sched& S, const Epi& E, const Pre& pre = Pre()) {
;     ...
;             PG8_LDB(B0, 1, 0); PG8_LDB(B1, 1, 1); PG8_SCHED; PG8_LDA(At, 1, 0); PG8_STAGE(PG8_SA(0, 1), a2 + hsA, voffA);
;             PG8_WAIT_V(8); PG8_WAIT_L(0); PG8_BAR; PG8_MMA(0, 0, At, B0); PG8_MMA(0, 1, At, B1); PG8_BAR; PG8_SCHED;
;             PG8_LDA(At, 1, 1); PG8_STAGE(PG8_SB(1, 0), b3, voffB); PG8_STAGE(PG8_SB(1, 1), b3 + hsB, voffB); PG8_STAGE(PG8_SA(1, 0), a3, voffA);
;             PG8_WAIT_V(8); PG8_WAIT_L(0); PG8_BAR; PG8_MMA(1, 0, At, B0); PG8_MMA(1, 1, At, B1); PG8_BAR; PG8_SCHED;
	s_add_i32 s82, s85, s7
	v_lshl_add_u64 v[192:193], v[192:193], 0, s[50:51]
	s_mov_b32 m0, s82
	ds_read_b128 v[160:163], v247 offset:49152
	ds_read_b128 v[164:167], v247 offset:50176
	ds_read_b128 v[168:171], v247 offset:51200
	ds_read_b128 v[172:175], v247 offset:52224
	ds_read_b128 v[176:179], v247 offset:53248
	ds_read_b128 v[180:183], v247 offset:54272
	ds_read_b128 v[184:187], v247 offset:55296
	ds_read_b128 v[188:191], v247 offset:56320
	global_load_lds_dwordx4 v[192:193], off
	s_add_i32 m0, s82, 0x2000
	s_add_u32 s30, s30, 0x40080
	v_lshl_add_u64 v[192:193], v[194:195], 0, s[50:51]
	s_addc_u32 s31, s31, 0
	s_add_i32 s82, s93, s7
	global_load_lds_dwordx4 v[192:193], off
	v_lshl_add_u64 v[192:193], s[30:31], 0, v[200:201]
	s_mov_b32 m0, s82
	s_nop 0
	global_load_lds_dwordx4 v[192:193], off
	v_lshl_add_u64 v[192:193], s[30:31], 0, v[216:217]
	s_add_i32 m0, s82, 0x2000
	s_nop 0
	global_load_lds_dwordx4 v[192:193], off
	v_lshl_add_u64 v[192:193], v[196:197], 0, s[50:51]
	s_mov_b32 m0, s8
	s_nop 0
	global_load_lds_dwordx4 v[192:193], off
	v_lshl_add_u64 v[192:193], v[198:199], 0, s[50:51]
	s_mov_b32 m0, s86
	s_nop 0
	global_load_lds_dwordx4 v[192:193], off
	s_waitcnt vmcnt(8)
	s_waitcnt lgkmcnt(0)
	s_barrier
	s_setprio 1
	s_waitcnt lgkmcnt(0)
	v_mfma_f32_16x16x32_bf16 v[60:63], v[64:67], v[160:163], v[60:63]
	v_mfma_f32_16x16x32_bf16 v[56:59], v[88:91], v[160:163], v[56:59]
	v_mfma_f32_16x16x32_bf16 v[44:47], v[64:67], v[168:171], v[44:47]
	v_mfma_f32_16x16x32_bf16 v[40:43], v[88:91], v[168:171], v[40:43]
	v_mfma_f32_16x16x32_bf16 v[28:31], v[64:67], v[176:179], v[28:31]
	v_mfma_f32_16x16x32_bf16 v[24:27], v[88:91], v[176:179], v[24:27]
	v_mfma_f32_16x16x32_bf16 v[12:15], v[64:67], v[184:187], v[12:15]
	v_mfma_f32_16x16x32_bf16 v[8:11], v[88:91], v[184:187], v[8:11]
	v_mfma_f32_16x16x32_bf16 v[60:63], v[76:79], v[164:167], v[60:63]
	v_mfma_f32_16x16x32_bf16 v[56:59], v[100:103], v[164:167], v[56:59]
	v_mfma_f32_16x16x32_bf16 v[44:47], v[76:79], v[172:175], v[44:47]
	v_mfma_f32_16x16x32_bf16 v[40:43], v[100:103], v[172:175], v[40:43]
	v_mfma_f32_16x16x32_bf16 v[28:31], v[76:79], v[180:183], v[28:31]
	v_mfma_f32_16x16x32_bf16 v[24:27], v[100:103], v[180:183], v[24:27]
	v_mfma_f32_16x16x32_bf16 v[12:15], v[76:79], v[188:191], v[12:15]
	v_mfma_f32_16x16x32_bf16 v[8:11], v[100:103], v[188:191], v[8:11]
	s_setprio 0
	s_setprio 1
	v_mfma_f32_16x16x32_bf16 v[52:55], v[112:115], v[160:163], v[52:55]
	v_mfma_f32_16x16x32_bf16 v[48:51], v[136:139], v[160:163], v[48:51]
	v_mfma_f32_16x16x32_bf16 v[36:39], v[112:115], v[168:171], v[36:39]
	v_mfma_f32_16x16x32_bf16 v[32:35], v[136:139], v[168:171], v[32:35]
	v_mfma_f32_16x16x32_bf16 v[20:23], v[112:115], v[176:179], v[20:23]
	v_mfma_f32_16x16x32_bf16 v[16:19], v[136:139], v[176:179], v[16:19]
	v_mfma_f32_16x16x32_bf16 v[4:7], v[112:115], v[184:187], v[4:7]
	v_mfma_f32_16x16x32_bf16 v[0:3], v[136:139], v[184:187], v[0:3]
	v_mfma_f32_16x16x32_bf16 v[52:55], v[124:127], v[164:167], v[52:55]
	v_mfma_f32_16x16x32_bf16 v[48:51], v[148:151], v[164:167], v[48:51]
	v_mfma_f32_16x16x32_bf16 v[36:39], v[124:127], v[172:175], v[36:39]
	v_mfma_f32_16x16x32_bf16 v[32:35], v[148:151], v[172:175], v[32:35]
	v_mfma_f32_16x16x32_bf16 v[20:23], v[124:127], v[180:183], v[20:23]
	v_mfma_f32_16x16x32_bf16 v[16:19], v[148:151], v[180:183], v[16:19]
	v_mfma_f32_16x16x32_bf16 v[4:7], v[124:127], v[188:191], v[4:7]
	v_mfma_f32_16x16x32_bf16 v[0:3], v[148:151], v[188:191], v[0:3]
	s_setprio 0
	s_barrier
	s_add_i32 s84, s84, 2
	s_add_u32 s47, s47, 0x100
	s_addc_u32 s58, s58, 0
	s_add_u32 vcc_lo, vcc_lo, 0x100
	s_addc_u32 vcc_hi, vcc_hi, 0
	s_cmp_gt_u32 s84, 13
	s_cbranch_scc0 .LBB0_697
	s_and_b64 vcc, exec, s[24:25]
	s_cbranch_vccz .LBB0_700
	s_barrier
